# GLA recurrence: o tiles / row sums staged in LDS and written out by the idle waves as full rows, tails interleaved with the state update; plus flat seam-0 barrier
# baseline (speedup 1.0000x reference)
; __device__ __forceinline__ unsigned cvt_pk_bf16(float lo, float hi) { unsigned r; asm volatile("v_cvt_pk_bf16_f32 %0, %1, %2" : "=v"(r) : "v"(lo), "v"(hi)); return r; }
; #define MFMA_SETTLE1(a) asm volatile("s_nop 15\n\ts_nop 15" : "+v"(a))
; __device__ __forceinline__ void gla_prompt_unit(const Args& a, unsigned char* lds, int unit, int tid) {
;     ...
;         const int vt = wave & 3, lt = wave >> 2;
;         f32x4 oacc = (f32x4){0.f, 0.f, 0.f, 0.f};
; #pragma unroll
;         for (int kk = 0; kk < 8; ++kk) { const bf16x8 af = *(const bf16x8*)(ST + (vt * 16 + r16) * 528 + kk * 64 + q4 * 16); const bf16x8 bfg = *(const bf16x8*)(QI + (lt * 16 + r16) * 528 + kk * 64 + q4 * 16);
;             oacc = __builtin_amdgcn_mfma_f32_16x16x32_bf16(af, bfg, oacc, 0, 0, 0); }
;         { const bf16x8 af = *(const bf16x8*)(VT + (vt * 16 + r16) * 80 + q4 * 16); const bf16x8 bfg = *(const bf16x8*)(AM + (lt * 16 + r16) * 80 + q4 * 16);
;           oacc = __builtin_amdgcn_mfma_f32_16x16x32_bf16(af, bfg, oacc, 0, 0, 0);
;           MFMA_SETTLE1(oacc);
;           const size_t row = row0 + lt * 16 + r16;
;           *(u32x2*)(OCAT + row * OC + 1024 + h * 512 + vs * 64 + vt * 16 + q4 * 4) = (u32x2){cvt_pk_bf16(oacc[0], oacc[1]), cvt_pk_bf16(oacc[2], oacc[3])};
;           float ss = (oacc[0] * oacc[0] + oacc[1] * oacc[1]) + (oacc[2] * oacc[2] + oacc[3] * oacc[3]); ss += __shfl_xor(ss, 16); ss += __shfl_xor(ss, 32);
;           if (lane < 16) GSS[(row * 4 + h) * 32 + vs * 4 + vt] = ss; }
.LBB0_497:
	s_or_b64 exec, exec, s[26:27]
	s_lshl_b32 s50, s33, 7
	s_mul_i32 s48, s36, 0x2f00000
	s_and_b32 s50, s50, 0xc00
	s_and_b32 s0, s44, 7
	s_mul_hi_i32 s49, s36, 0x2f00000
	s_or_b32 s48, s48, s50
	v_or_b32_e32 v108, s34, v70
	s_lshl_b32 s34, s33, 4
	s_lshl_b64 s[26:27], s[30:31], 19
	s_lshl_b32 s0, s0, 4
	v_lshl_add_u64 v[2:3], s[48:49], 0, v[86:87]
	s_lshl_b64 s[48:49], s[30:31], 17
	s_lshl_b64 s[30:31], s[30:31], 16
	s_and_b32 s34, s34, 0x180
	v_lshl_add_u64 v[106:107], v[90:91], 0, s[30:31]
	s_lshl_b64 s[30:31], s[36:37], 20
	s_or_b32 s0, s0, s34
	v_lshlrev_b64 v[10:11], 1, v[102:103]
	s_or_b32 s30, s30, s0
	s_mul_i32 s0, s36, 0xc00000
	v_mul_lo_u32 v1, v9, s3
	v_lshl_add_u64 v[2:3], v[2:3], 0, v[10:11]
	v_lshlrev_b32_e32 v8, 1, v8
	v_mov_b32_e32 v9, v0
	v_lshl_add_u64 v[110:111], s[30:31], 0, v[92:93]
	s_mul_hi_i32 s31, s36, 0xc00000
	s_or_b32 s30, s0, s50
	v_lshl_add_u64 v[2:3], v[2:3], 0, v[8:9]
	v_lshl_add_u64 v[8:9], s[30:31], 0, v[94:95]
	v_lshl_add_u64 v[112:113], v[8:9], 0, v[10:11]
	v_mov_b32_e32 v8, 0
	v_lshl_add_u64 v[104:105], v[88:89], 0, s[48:49]
	v_mov_b32_e32 v109, s35
	s_mov_b32 s0, 63
	v_mov_b32_e32 v9, v8
	v_mov_b32_e32 v10, v8
	v_mov_b32_e32 v11, v8
	v_mov_b32_e32 v12, v8
	v_mov_b32_e32 v13, v8
	v_mov_b32_e32 v14, v8
	v_mov_b32_e32 v15, v8
	v_mov_b32_e32 v16, v8
	v_mov_b32_e32 v17, v8
	v_mov_b32_e32 v18, v8
	v_mov_b32_e32 v19, v8
	v_mov_b32_e32 v20, v8
	v_mov_b32_e32 v21, v8
	v_mov_b32_e32 v22, v8
	v_mov_b32_e32 v23, v8
	v_mov_b32_e32 v24, v8
	v_mov_b32_e32 v25, v8
	v_mov_b32_e32 v26, v8
	v_mov_b32_e32 v27, v8
	v_mov_b32_e32 v28, v8
	v_mov_b32_e32 v29, v8
	v_mov_b32_e32 v30, v8
	v_mov_b32_e32 v31, v8
	v_mov_b32_e32 v32, v8
	v_mov_b32_e32 v33, v8
	v_mov_b32_e32 v34, v8
	v_mov_b32_e32 v35, v8
	v_mov_b32_e32 v36, v8
	v_mov_b32_e32 v37, v8
	v_mov_b32_e32 v38, v8
	v_mov_b32_e32 v39, v8
	v_and_b32_e32 v97, 15, v186
	v_lshrrev_b32_e32 v99, 4, v186
	v_mul_u32_u24_e32 v222, 0x210, v97
	v_lshl_add_u32 v222, v99, 4, v222
	v_mul_u32_u24_e32 v101, 0x50, v97
	v_lshl_add_u32 v101, v99, 4, v101
	v_add_u32_e32 v223, 0x16c00, v101
	v_add_u32_e32 v225, 0x8400, v101
	v_mul_u32_u24_e32 v141, 0x500, v148
	v_add_u32_e32 v224, v141, v101
	v_add_u32_e32 v224, 0x15800, v224
	v_lshlrev_b32_e32 v226, 4, v99
	v_add_u32_e32 v226, 0x18000, v226
	v_xor_b32_e32 v227, 16, v186
	v_lshlrev_b32_e32 v227, 2, v227
	v_xor_b32_e32 v228, 32, v186
	v_lshlrev_b32_e32 v228, 2, v228
	v_and_b32_e32 v141, 1, v188
	v_lshlrev_b32_e32 v141, 4, v141
	v_bfe_u32 v229, v188, 1, 1
	v_mul_u32_u24_e32 v229, 24, v229
	v_sub_u32_e32 v141, v141, v229
	v_add_u32_e32 v230, v126, v141
	v_add_u32_e32 v234, v128, v141
	v_readfirstlane_b32 s96, v148
	s_mov_b64 s[98:99], 0x18000
	s_mov_b64 s[92:93], 0x2000
	v_mov_b32_e32 v190, 0
	v_mov_b32_e32 v191, 0
	v_mov_b32_e32 v192, 0
	v_mov_b32_e32 v193, 0
	v_mov_b32_e32 v194, 0
	v_mov_b32_e32 v195, 0
	v_mov_b32_e32 v196, 0
	v_mov_b32_e32 v197, 0
	v_mov_b32_e32 v198, 0
	v_mov_b32_e32 v199, 0
	v_mov_b32_e32 v200, 0
	v_mov_b32_e32 v201, 0
	v_mov_b32_e32 v202, 0
	v_mov_b32_e32 v203, 0
	v_mov_b32_e32 v204, 0
	v_mov_b32_e32 v205, 0
	v_mov_b32_e32 v206, 0
	v_mov_b32_e32 v207, 0
	v_mov_b32_e32 v208, 0
	v_mov_b32_e32 v209, 0
	v_mov_b32_e32 v210, 0
	v_mov_b32_e32 v211, 0
	v_mov_b32_e32 v212, 0
	v_mov_b32_e32 v213, 0
	v_mov_b32_e32 v214, 0
	v_mov_b32_e32 v215, 0
	v_mov_b32_e32 v216, 0
	v_mov_b32_e32 v217, 0
	v_mov_b32_e32 v218, 0
	v_mov_b32_e32 v219, 0
	v_mov_b32_e32 v220, 0
	v_mov_b32_e32 v221, 0
	v_mul_u32_u24_e32 v231, 0x90, v97
	v_lshl_add_u32 v231, v148, 5, v231
	v_lshl_add_u32 v231, v99, 3, v231
	v_add_u32_e32 v231, 0xd400, v231
	v_lshlrev_b32_e32 v235, 4, v97
	v_lshl_add_u32 v235, v148, 2, v235
	v_add_u32_e32 v235, 0x11400, v235
	s_cmp_lt_u32 s96, 4
	s_cbranch_scc1 .Lgn_init_done
	v_add_u32_e32 v8, 0xffffff00, v188
	v_lshrrev_b32_e32 v9, 3, v8
	v_and_b32_e32 v14, 7, v8
	v_mul_u32_u24_e32 v8, 0x90, v9
	v_lshl_add_u32 v8, v14, 4, v8
	v_add_u32_e32 v8, 0xd400, v8
	s_ashr_i32 s54, s33, 3
	s_lshr_b32 s55, s54, 2
	s_and_b32 s56, s54, 3
	s_and_b32 s57, s33, 7
	s_mul_i32 s58, s55, 0xc00000
	s_lshl_b32 s59, s56, 10
	s_add_u32 s58, s58, s59
	s_lshl_b32 s59, s57, 7
	s_add_u32 s58, s58, s59
	s_add_u32 s58, s58, 0x24a00800
	s_add_u32 s60, s86, s58
	s_addc_u32 s61, s87, 0
	v_mul_u32_u24_e32 v10, 0x1800, v9
	v_lshl_add_u32 v10, v14, 4, v10
	v_mov_b32_e32 v11, 0
	v_lshl_add_u64 v[10:11], s[60:61], 0, v[10:11]
	s_lshl_b32 s58, s55, 20
	s_lshl_b32 s59, s56, 7
	s_add_u32 s58, s58, s59
	s_lshl_b32 s59, s57, 4
	s_add_u32 s58, s58, s59
	s_add_u32 s58, s58, 0x33700000
	s_add_u32 s60, s86, s58
	s_addc_u32 s61, s87, 0
	v_lshlrev_b32_e32 v12, 9, v186
	v_mov_b32_e32 v13, 0
	v_lshl_add_u64 v[12:13], s[60:61], 0, v[12:13]
	v_lshlrev_b32_e32 v9, 4, v186
	v_add_u32_e32 v9, 0x11400, v9
.Lgn_init_done:
.Lgn_loop:
.Lgn_a499:
	s_waitcnt vmcnt(3)
	ds_write2_b64 v230, v[48:49], v[50:51] offset1:2
	s_waitcnt vmcnt(2)
	ds_write_b128 v127, v[52:55] offset:33792
	s_waitcnt vmcnt(1)
	ds_write2_b64 v234, v[56:57], v[58:59] offset1:2
	s_waitcnt vmcnt(0)
	ds_write_b128 v129, v[60:63] offset:33792
	s_and_saveexec_b64 s[30:31], s[4:5]
	s_cbranch_execnz .Lgn_a509
	s_or_b64 exec, exec, s[30:31]
	s_and_saveexec_b64 s[30:31], s[6:7]
	s_cbranch_execnz .Lgn_a510

; __device__ __forceinline__ unsigned cvt_pk_bf16(float lo, float hi) { unsigned r; asm volatile("v_cvt_pk_bf16_f32 %0, %1, %2" : "=v"(r) : "v"(lo), "v"(hi)); return r; }
; #define MFMA_SETTLE1(a) asm volatile("s_nop 15\n\ts_nop 15" : "+v"(a))
; #define LBAR() asm volatile("s_waitcnt lgkmcnt(0)\n\ts_barrier" ::: "memory")
; __device__ __forceinline__ void gla_prompt_unit(const Args& a, unsigned char* lds, int unit, int tid) {
;     ...
; #pragma unroll
;         for (int kk = 0; kk < 8; ++kk) { const bf16x8 af = *(const bf16x8*)(ST + (vt * 16 + r16) * 528 + kk * 64 + q4 * 16); const bf16x8 bfg = *(const bf16x8*)(QI + (lt * 16 + r16) * 528 + kk * 64 + q4 * 16);
;             oacc = __builtin_amdgcn_mfma_f32_16x16x32_bf16(af, bfg, oacc, 0, 0, 0); }
;         { const bf16x8 af = *(const bf16x8*)(VT + (vt * 16 + r16) * 80 + q4 * 16); const bf16x8 bfg = *(const bf16x8*)(AM + (lt * 16 + r16) * 80 + q4 * 16);
;           oacc = __builtin_amdgcn_mfma_f32_16x16x32_bf16(af, bfg, oacc, 0, 0, 0);
;           MFMA_SETTLE1(oacc);
;           const size_t row = row0 + lt * 16 + r16;
;           *(u32x2*)(OCAT + row * OC + 1024 + h * 512 + vs * 64 + vt * 16 + q4 * 4) = (u32x2){cvt_pk_bf16(oacc[0], oacc[1]), cvt_pk_bf16(oacc[2], oacc[3])};
;           float ss = (oacc[0] * oacc[0] + oacc[1] * oacc[1]) + (oacc[2] * oacc[2] + oacc[3] * oacc[3]); ss += __shfl_xor(ss, 16); ss += __shfl_xor(ss, 32);
;           if (lane < 16) GSS[(row * 4 + h) * 32 + vs * 4 + vt] = ss; }
;         LBAR();
; #pragma unroll
;         for (int k2 = 0; k2 < 2; ++k2) { const int kt = wave * 2 + k2; const f32x4 dec4 = *(const f32x4*)(DEC + kt * 16 + q4 * 4); const bf16x8 af = *(const bf16x8*)(KDT + (kt * 16 + r16) * 80 + q4 * 16);
; #pragma unroll
;             for (int v2 = 0; v2 < 4; ++v2) { const bf16x8 bfg = *(const bf16x8*)(VT + (v2 * 16 + r16) * 80 + q4 * 16);
;                 sacc[k2][v2] = __builtin_amdgcn_mfma_f32_16x16x32_bf16(af, bfg, sacc[k2][v2] * dec4, 0, 0, 0); } }
.Lgn_a507:
	s_or_b64 exec, exec, s[30:31]
	s_waitcnt lgkmcnt(0)
	s_barrier
	s_cmp_gt_u32 s96, 3
	s_cbranch_scc1 .Lgn_store
	ds_read_b128 v[178:181], v224
	ds_read_b128 v[162:165], v222
	ds_read_b128 v[166:169], v222 offset:8448
	ds_read_b128 v[170:173], v222 offset:64
	ds_read_b128 v[174:177], v222 offset:8512
	ds_read_b128 v[236:239], v222 offset:128
	ds_read_b128 v[240:243], v222 offset:8576
	ds_read_b128 v[244:247], v222 offset:192
	ds_read_b128 v[250:253], v222 offset:8640
	v_cvt_pk_bf16_f32 v150, v8, v9
	v_cvt_pk_bf16_f32 v151, v10, v11
	v_cvt_pk_bf16_f32 v152, v12, v13
	v_cvt_pk_bf16_f32 v153, v14, v15
	s_waitcnt lgkmcnt(6)
	s_nop 0
	v_mfma_f32_16x16x32_bf16 v[142:145], v[150:153], v[162:165], 0
	v_mfma_f32_16x16x32_bf16 v[158:161], v[150:153], v[166:169], 0
	ds_read_b128 v[162:165], v222 offset:256
	ds_read_b128 v[166:169], v222 offset:8704
	v_cvt_pk_bf16_f32 v154, v16, v17
	v_cvt_pk_bf16_f32 v155, v18, v19
	v_cvt_pk_bf16_f32 v156, v20, v21
	v_cvt_pk_bf16_f32 v157, v22, v23
	s_waitcnt lgkmcnt(6)
	s_nop 0
	v_mfma_f32_16x16x32_bf16 v[142:145], v[154:157], v[170:173], v[142:145]
	v_mfma_f32_16x16x32_bf16 v[158:161], v[154:157], v[174:177], v[158:161]
	ds_read_b128 v[170:173], v222 offset:320
	ds_read_b128 v[174:177], v222 offset:8768
	v_cvt_pk_bf16_f32 v150, v24, v25
	v_cvt_pk_bf16_f32 v151, v26, v27
	v_cvt_pk_bf16_f32 v152, v28, v29
	v_cvt_pk_bf16_f32 v153, v30, v31
	s_waitcnt lgkmcnt(6)
	s_nop 0
	v_mfma_f32_16x16x32_bf16 v[142:145], v[150:153], v[236:239], v[142:145]
	v_mfma_f32_16x16x32_bf16 v[158:161], v[150:153], v[240:243], v[158:161]
	ds_read_b128 v[236:239], v222 offset:384
	ds_read_b128 v[240:243], v222 offset:8832
	v_cvt_pk_bf16_f32 v154, v32, v33
	v_cvt_pk_bf16_f32 v155, v34, v35
	v_cvt_pk_bf16_f32 v156, v36, v37
	v_cvt_pk_bf16_f32 v157, v38, v39
	s_waitcnt lgkmcnt(6)
	s_nop 0
	v_mfma_f32_16x16x32_bf16 v[142:145], v[154:157], v[244:247], v[142:145]
	v_mfma_f32_16x16x32_bf16 v[158:161], v[154:157], v[250:253], v[158:161]
	ds_read_b128 v[244:247], v222 offset:448
	ds_read_b128 v[250:253], v222 offset:8896
	v_cvt_pk_bf16_f32 v150, v190, v191
	v_cvt_pk_bf16_f32 v151, v192, v193
	v_cvt_pk_bf16_f32 v152, v194, v195
	v_cvt_pk_bf16_f32 v153, v196, v197
	s_waitcnt lgkmcnt(6)
	s_nop 0
	v_mfma_f32_16x16x32_bf16 v[142:145], v[150:153], v[162:165], v[142:145]
	v_mfma_f32_16x16x32_bf16 v[158:161], v[150:153], v[166:169], v[158:161]
	ds_read_b128 v[162:165], v223
	ds_read_b128 v[166:169], v223 offset:1280
	v_cvt_pk_bf16_f32 v154, v198, v199
	v_cvt_pk_bf16_f32 v155, v200, v201
	v_cvt_pk_bf16_f32 v156, v202, v203
	v_cvt_pk_bf16_f32 v157, v204, v205
	s_waitcnt lgkmcnt(6)
	s_nop 0
	v_mfma_f32_16x16x32_bf16 v[142:145], v[154:157], v[170:173], v[142:145]
	v_mfma_f32_16x16x32_bf16 v[158:161], v[154:157], v[174:177], v[158:161]
	v_cvt_pk_bf16_f32 v150, v206, v207
	v_cvt_pk_bf16_f32 v151, v208, v209
	v_cvt_pk_bf16_f32 v152, v210, v211
	v_cvt_pk_bf16_f32 v153, v212, v213
	s_waitcnt lgkmcnt(4)
	s_nop 0
	v_mfma_f32_16x16x32_bf16 v[142:145], v[150:153], v[236:239], v[142:145]
	v_mfma_f32_16x16x32_bf16 v[158:161], v[150:153], v[240:243], v[158:161]
	v_cvt_pk_bf16_f32 v154, v214, v215
	v_cvt_pk_bf16_f32 v155, v216, v217
	v_cvt_pk_bf16_f32 v156, v218, v219
	v_cvt_pk_bf16_f32 v157, v220, v221
	s_waitcnt lgkmcnt(2)
	s_nop 0
	v_mfma_f32_16x16x32_bf16 v[142:145], v[154:157], v[244:247], v[142:145]
	v_mfma_f32_16x16x32_bf16 v[158:161], v[154:157], v[250:253], v[158:161]
	s_waitcnt lgkmcnt(0)
	v_mfma_f32_16x16x32_bf16 v[142:145], v[178:181], v[162:165], v[142:145]
	v_mfma_f32_16x16x32_bf16 v[158:161], v[178:181], v[166:169], v[158:161]
	ds_read_b128 v[170:173], v225
	ds_read_b128 v[174:177], v226
	ds_read_b128 v[236:239], v225 offset:1280
	ds_read_b128 v[240:243], v226 offset:64
	ds_read_b128 v[244:247], v225 offset:2560
	ds_read_b128 v[250:253], v226 offset:128
	ds_read_b128 v[162:165], v225 offset:3840
	ds_read_b128 v[166:169], v226 offset:192
	s_waitcnt lgkmcnt(6)
	v_pk_mul_f32 v[8:9], v[8:9], v[174:175]
	v_pk_mul_f32 v[10:11], v[10:11], v[176:177]
	s_nop 1
	v_mfma_f32_16x16x32_bf16 v[8:11], v[170:173], v[178:181], v[8:11]
	ds_read_b128 v[170:173], v225 offset:5120
	ds_read_b128 v[174:177], v226 offset:256
	s_waitcnt lgkmcnt(6)
	v_pk_mul_f32 v[12:13], v[12:13], v[240:241]
	v_pk_mul_f32 v[14:15], v[14:15], v[242:243]
	s_nop 1
	v_mfma_f32_16x16x32_bf16 v[12:15], v[236:239], v[178:181], v[12:15]
	ds_read_b128 v[236:239], v225 offset:6400
	ds_read_b128 v[240:243], v226 offset:320
	v_mul_f32_e32 v150, v143, v143
	v_mul_f32_e32 v151, v145, v145
	v_fmac_f32_e32 v150, v142, v142
	v_fmac_f32_e32 v151, v144, v144
	v_add_f32_e32 v150, v150, v151
	ds_bpermute_b32 v151, v227, v150
	v_mul_f32_e32 v152, v159, v159
	v_mul_f32_e32 v153, v161, v161
	v_fmac_f32_e32 v152, v158, v158
	v_fmac_f32_e32 v153, v160, v160
	v_add_f32_e32 v152, v152, v153
	ds_bpermute_b32 v153, v227, v152
	s_waitcnt lgkmcnt(8)
; __device__ __forceinline__ unsigned cvt_pk_bf16(float lo, float hi) { unsigned r; asm volatile("v_cvt_pk_bf16_f32 %0, %1, %2" : "=v"(r) : "v"(lo), "v"(hi)); return r; }
; #define LBAR() asm volatile("s_waitcnt lgkmcnt(0)\n\ts_barrier" ::: "memory")
; __device__ __forceinline__ void gla_prompt_unit(const Args& a, unsigned char* lds, int unit, int tid) {
;     ...
;           const size_t row = row0 + lt * 16 + r16;
;           *(u32x2*)(OCAT + row * OC + 1024 + h * 512 + vs * 64 + vt * 16 + q4 * 4) = (u32x2){cvt_pk_bf16(oacc[0], oacc[1]), cvt_pk_bf16(oacc[2], oacc[3])};
;           float ss = (oacc[0] * oacc[0] + oacc[1] * oacc[1]) + (oacc[2] * oacc[2] + oacc[3] * oacc[3]); ss += __shfl_xor(ss, 16); ss += __shfl_xor(ss, 32);
;           if (lane < 16) GSS[(row * 4 + h) * 32 + vs * 4 + vt] = ss; }
;         LBAR();
; #pragma unroll
;         for (int k2 = 0; k2 < 2; ++k2) { const int kt = wave * 2 + k2; const f32x4 dec4 = *(const f32x4*)(DEC + kt * 16 + q4 * 4); const bf16x8 af = *(const bf16x8*)(KDT + (kt * 16 + r16) * 80 + q4 * 16);
; #pragma unroll
;             for (int v2 = 0; v2 < 4; ++v2) { const bf16x8 bfg = *(const bf16x8*)(VT + (v2 * 16 + r16) * 80 + q4 * 16);
;                 sacc[k2][v2] = __builtin_amdgcn_mfma_f32_16x16x32_bf16(af, bfg, sacc[k2][v2] * dec4, 0, 0, 0); } }
	v_pk_mul_f32 v[16:17], v[16:17], v[250:251]
	v_pk_mul_f32 v[18:19], v[18:19], v[252:253]
	s_nop 1
	v_mfma_f32_16x16x32_bf16 v[16:19], v[244:247], v[178:181], v[16:19]
	ds_read_b128 v[244:247], v225 offset:7680
	ds_read_b128 v[250:253], v226 offset:384
	s_waitcnt lgkmcnt(8)
	v_pk_mul_f32 v[20:21], v[20:21], v[166:167]
	v_pk_mul_f32 v[22:23], v[22:23], v[168:169]
	s_nop 1
	v_mfma_f32_16x16x32_bf16 v[20:23], v[162:165], v[178:181], v[20:23]
	ds_read_b128 v[162:165], v225 offset:8960
	ds_read_b128 v[166:169], v226 offset:448
	v_cvt_pk_bf16_f32 v154, v142, v143
	v_cvt_pk_bf16_f32 v155, v144, v145
	v_cvt_pk_bf16_f32 v156, v158, v159
	v_cvt_pk_bf16_f32 v157, v160, v161
	s_and_b32 s97, s0, 1
	s_xor_b32 s97, s97, 1
	s_lshl_b32 s97, s97, 13
	v_add_u32_e32 v229, s97, v231
	ds_write_b64 v229, v[154:155]
	ds_write_b64 v229, v[156:157] offset:2304
	s_waitcnt lgkmcnt(10)
	v_pk_mul_f32 v[24:25], v[24:25], v[174:175]
	v_pk_mul_f32 v[26:27], v[26:27], v[176:177]
	s_nop 1
	v_mfma_f32_16x16x32_bf16 v[24:27], v[170:173], v[178:181], v[24:27]
	ds_read_b128 v[170:173], v225 offset:10240
	ds_read_b128 v[174:177], v226 offset:512
	s_waitcnt lgkmcnt(10)
	v_pk_mul_f32 v[28:29], v[28:29], v[240:241]
	v_pk_mul_f32 v[30:31], v[30:31], v[242:243]
	s_nop 1
	v_mfma_f32_16x16x32_bf16 v[28:31], v[236:239], v[178:181], v[28:31]
	ds_read_b128 v[236:239], v225 offset:11520
	ds_read_b128 v[240:243], v226 offset:576
	s_waitcnt lgkmcnt(8)
	v_pk_mul_f32 v[32:33], v[32:33], v[250:251]
	v_pk_mul_f32 v[34:35], v[34:35], v[252:253]
	s_nop 1
	v_mfma_f32_16x16x32_bf16 v[32:35], v[244:247], v[178:181], v[32:35]
	ds_read_b128 v[244:247], v225 offset:12800
	ds_read_b128 v[250:253], v226 offset:640
	v_add_f32_e32 v150, v150, v151
	v_add_f32_e32 v152, v152, v153
	ds_bpermute_b32 v151, v228, v150
	ds_bpermute_b32 v153, v228, v152
	s_waitcnt lgkmcnt(10)
	v_pk_mul_f32 v[36:37], v[36:37], v[166:167]
	v_pk_mul_f32 v[38:39], v[38:39], v[168:169]
	s_nop 1
	v_mfma_f32_16x16x32_bf16 v[36:39], v[162:165], v[178:181], v[36:39]
	ds_read_b128 v[162:165], v225 offset:14080
	ds_read_b128 v[166:169], v226 offset:704
	s_waitcnt lgkmcnt(8)
	v_pk_mul_f32 v[190:191], v[190:191], v[174:175]
	v_pk_mul_f32 v[192:193], v[192:193], v[176:177]
	s_nop 1
	v_mfma_f32_16x16x32_bf16 v[190:193], v[170:173], v[178:181], v[190:193]
	ds_read_b128 v[170:173], v225 offset:15360
	ds_read_b128 v[174:177], v226 offset:768
	s_waitcnt lgkmcnt(8)
	v_pk_mul_f32 v[194:195], v[194:195], v[240:241]
	v_pk_mul_f32 v[196:197], v[196:197], v[242:243]
	s_nop 1
	v_mfma_f32_16x16x32_bf16 v[194:197], v[236:239], v[178:181], v[194:197]
	ds_read_b128 v[236:239], v225 offset:16640
	ds_read_b128 v[240:243], v226 offset:832
	s_waitcnt lgkmcnt(8)
	v_pk_mul_f32 v[198:199], v[198:199], v[250:251]
	v_pk_mul_f32 v[200:201], v[200:201], v[252:253]
	s_nop 1
	v_mfma_f32_16x16x32_bf16 v[198:201], v[244:247], v[178:181], v[198:201]
	ds_read_b128 v[244:247], v225 offset:17920
	ds_read_b128 v[250:253], v226 offset:896
	s_waitcnt lgkmcnt(6)
	v_pk_mul_f32 v[202:203], v[202:203], v[166:167]
	v_pk_mul_f32 v[204:205], v[204:205], v[168:169]
	s_nop 1
	v_mfma_f32_16x16x32_bf16 v[202:205], v[162:165], v[178:181], v[202:205]
	ds_read_b128 v[162:165], v225 offset:19200
	ds_read_b128 v[166:169], v226 offset:960
	v_add_f32_e32 v150, v150, v151
	v_add_f32_e32 v152, v152, v153
	s_lshr_b32 s97, s97, 4
	v_add_u32_e32 v229, s97, v235
	s_and_saveexec_b64 s[30:31], s[12:13]
	ds_write_b32 v229, v150
	ds_write_b32 v229, v152 offset:256
	s_or_b64 exec, exec, s[30:31]
	s_waitcnt lgkmcnt(8)
	v_pk_mul_f32 v[206:207], v[206:207], v[174:175]
	v_pk_mul_f32 v[208:209], v[208:209], v[176:177]
	s_nop 1
	v_mfma_f32_16x16x32_bf16 v[206:209], v[170:173], v[178:181], v[206:209]
	s_waitcnt lgkmcnt(6)
	v_pk_mul_f32 v[210:211], v[210:211], v[240:241]
	v_pk_mul_f32 v[212:213], v[212:213], v[242:243]
	s_nop 1
	v_mfma_f32_16x16x32_bf16 v[210:213], v[236:239], v[178:181], v[210:213]
	s_waitcnt lgkmcnt(4)
	v_pk_mul_f32 v[214:215], v[214:215], v[250:251]
	v_pk_mul_f32 v[216:217], v[216:217], v[252:253]
	s_nop 1
	v_mfma_f32_16x16x32_bf16 v[214:217], v[244:247], v[178:181], v[214:217]
	s_waitcnt lgkmcnt(2)
	v_pk_mul_f32 v[218:219], v[218:219], v[166:167]
	v_pk_mul_f32 v[220:221], v[220:221], v[168:169]
	s_nop 1
	v_mfma_f32_16x16x32_bf16 v[218:221], v[162:165], v[178:181], v[218:221]
	s_branch .Lgn_skip
.Lgn_store:
	s_cmp_eq_u32 s0, 63
	s_cbranch_scc1 .Lgn_skip
	s_and_b32 s97, s0, 1
	s_lshl_b32 s97, s97, 13
	v_add_u32_e32 v14, s97, v8
	ds_read_b128 v[16:19], v14
	s_lshr_b32 s97, s97, 4
	v_add_u32_e32 v15, s97, v9
	ds_read_b128 v[20:23], v15
	s_waitcnt lgkmcnt(0)
	global_store_dwordx4 v[10:11], v[16:19], off
	s_cmp_lg_u32 s96, 4
	s_cbranch_scc1 .Lgn_st1
	v_cmp_gt_u32_e32 vcc, 32, v186
	s_and_saveexec_b64 s[30:31], vcc
	global_store_dwordx4 v[12:13], v[20:23], off
	s_or_b64 exec, exec, s[30:31]
.Lgn_st1:
	v_lshl_add_u64 v[10:11], v[10:11], 0, s[22:23]
	v_lshl_add_u64 v[12:13], v[12:13], 0, s[20:21]

; __device__ __forceinline__ unsigned cvt_pk_bf16(float lo, float hi) { unsigned r; asm volatile("v_cvt_pk_bf16_f32 %0, %1, %2" : "=v"(r) : "v"(lo), "v"(hi)); return r; }
; __device__ __forceinline__ void gla_prompt_unit(const Args& a, unsigned char* lds, int unit, int tid) {
;     ...
;           const size_t row = row0 + lt * 16 + r16;
;           *(u32x2*)(OCAT + row * OC + 1024 + h * 512 + vs * 64 + vt * 16 + q4 * 4) = (u32x2){cvt_pk_bf16(oacc[0], oacc[1]), cvt_pk_bf16(oacc[2], oacc[3])};
;           float ss = (oacc[0] * oacc[0] + oacc[1] * oacc[1]) + (oacc[2] * oacc[2] + oacc[3] * oacc[3]); ss += __shfl_xor(ss, 16); ss += __shfl_xor(ss, 32);
;           if (lane < 16) GSS[(row * 4 + h) * 32 + vs * 4 + vt] = ss; }
;     ...
;     float* SP = a.out + OUT_SP + (size_t)bh * 256 * 512;
; #pragma unroll
;     for (int k2 = 0; k2 < 2; ++k2)
; #pragma unroll
;         for (int v2 = 0; v2 < 4; ++v2)
; #pragma unroll
;             for (int j = 0; j < 4; ++j) SP[(size_t)((wave * 2 + k2) * 16 + q4 * 4 + j) * 512 + vs * 64 + v2 * 16 + r16] = sacc[k2][v2][j];
.Lgn_fin:
	s_cmp_gt_u32 s96, 3
	s_cbranch_scc1 .Lgn_flush
	s_ashr_i32 s54, s33, 3
	s_lshl_b32 s54, s54, 19
	s_and_b32 s55, s33, 7
	s_lshl_b32 s55, s55, 8
	s_add_i32 s54, s54, s55
	s_add_u32 s54, s38, s54
	s_addc_u32 s55, s39, 0
	s_mov_b64 s[58:59], 0x8000
	s_mov_b64 s[60:61], 0x1000
	v_lshlrev_b32_e32 v232, 13, v99
	v_lshl_add_u32 v232, v148, 6, v232
	v_lshl_add_u32 v232, v97, 2, v232
	v_mov_b32_e32 v233, 0
	v_lshl_add_u64 v[236:237], s[54:55], 0, v[232:233]
	v_lshl_add_u64 v[238:239], v[236:237], 0, s[60:61]
	global_store_dword v[236:237], v8, off
	global_store_dword v[236:237], v9, off offset:2048
	global_store_dword v[238:239], v10, off
	global_store_dword v[238:239], v11, off offset:2048
	v_lshl_add_u64 v[236:237], v[236:237], 0, s[58:59]
	v_lshl_add_u64 v[238:239], v[238:239], 0, s[58:59]
	global_store_dword v[236:237], v12, off
	global_store_dword v[236:237], v13, off offset:2048
	global_store_dword v[238:239], v14, off
	global_store_dword v[238:239], v15, off offset:2048
	v_lshl_add_u64 v[236:237], v[236:237], 0, s[58:59]
	v_lshl_add_u64 v[238:239], v[238:239], 0, s[58:59]
	global_store_dword v[236:237], v16, off
	global_store_dword v[236:237], v17, off offset:2048
	global_store_dword v[238:239], v18, off
	global_store_dword v[238:239], v19, off offset:2048
	v_lshl_add_u64 v[236:237], v[236:237], 0, s[58:59]
	v_lshl_add_u64 v[238:239], v[238:239], 0, s[58:59]
	global_store_dword v[236:237], v20, off
	global_store_dword v[236:237], v21, off offset:2048
	global_store_dword v[238:239], v22, off
	global_store_dword v[238:239], v23, off offset:2048
	v_lshl_add_u64 v[236:237], v[236:237], 0, s[58:59]
	v_lshl_add_u64 v[238:239], v[238:239], 0, s[58:59]
	global_store_dword v[236:237], v24, off
	global_store_dword v[236:237], v25, off offset:2048
	global_store_dword v[238:239], v26, off
	global_store_dword v[238:239], v27, off offset:2048
	v_lshl_add_u64 v[236:237], v[236:237], 0, s[58:59]
	v_lshl_add_u64 v[238:239], v[238:239], 0, s[58:59]
	global_store_dword v[236:237], v28, off
	global_store_dword v[236:237], v29, off offset:2048
	global_store_dword v[238:239], v30, off
	global_store_dword v[238:239], v31, off offset:2048
	v_lshl_add_u64 v[236:237], v[236:237], 0, s[58:59]
	v_lshl_add_u64 v[238:239], v[238:239], 0, s[58:59]
	global_store_dword v[236:237], v32, off
	global_store_dword v[236:237], v33, off offset:2048
	global_store_dword v[238:239], v34, off
	global_store_dword v[238:239], v35, off offset:2048
	v_lshl_add_u64 v[236:237], v[236:237], 0, s[58:59]
	v_lshl_add_u64 v[238:239], v[238:239], 0, s[58:59]
	global_store_dword v[236:237], v36, off
	global_store_dword v[236:237], v37, off offset:2048
	global_store_dword v[238:239], v38, off
	global_store_dword v[238:239], v39, off offset:2048
	v_lshl_add_u64 v[236:237], v[236:237], 0, s[58:59]
	v_lshl_add_u64 v[238:239], v[238:239], 0, s[58:59]
	global_store_dword v[236:237], v190, off
	global_store_dword v[236:237], v191, off offset:2048
	global_store_dword v[238:239], v192, off
	global_store_dword v[238:239], v193, off offset:2048
	v_lshl_add_u64 v[236:237], v[236:237], 0, s[58:59]
	v_lshl_add_u64 v[238:239], v[238:239], 0, s[58:59]
	global_store_dword v[236:237], v194, off
	global_store_dword v[236:237], v195, off offset:2048
	global_store_dword v[238:239], v196, off
	global_store_dword v[238:239], v197, off offset:2048
	v_lshl_add_u64 v[236:237], v[236:237], 0, s[58:59]
	v_lshl_add_u64 v[238:239], v[238:239], 0, s[58:59]
	global_store_dword v[236:237], v198, off
	global_store_dword v[236:237], v199, off offset:2048
	global_store_dword v[238:239], v200, off
	global_store_dword v[238:239], v201, off offset:2048
	v_lshl_add_u64 v[236:237], v[236:237], 0, s[58:59]
	v_lshl_add_u64 v[238:239], v[238:239], 0, s[58:59]
	global_store_dword v[236:237], v202, off
	global_store_dword v[236:237], v203, off offset:2048
	global_store_dword v[238:239], v204, off
	global_store_dword v[238:239], v205, off offset:2048
	v_lshl_add_u64 v[236:237], v[236:237], 0, s[58:59]
	v_lshl_add_u64 v[238:239], v[238:239], 0, s[58:59]
	global_store_dword v[236:237], v206, off
	global_store_dword v[236:237], v207, off offset:2048
	global_store_dword v[238:239], v208, off
	global_store_dword v[238:239], v209, off offset:2048
	v_lshl_add_u64 v[236:237], v[236:237], 0, s[58:59]
	v_lshl_add_u64 v[238:239], v[238:239], 0, s[58:59]
	global_store_dword v[236:237], v210, off
	global_store_dword v[236:237], v211, off offset:2048
	global_store_dword v[238:239], v212, off
	global_store_dword v[238:239], v213, off offset:2048
	v_lshl_add_u64 v[236:237], v[236:237], 0, s[58:59]
	v_lshl_add_u64 v[238:239], v[238:239], 0, s[58:59]
	global_store_dword v[236:237], v214, off
	global_store_dword v[236:237], v215, off offset:2048
	global_store_dword v[238:239], v216, off
	global_store_dword v[238:239], v217, off offset:2048
	v_lshl_add_u64 v[236:237], v[236:237], 0, s[58:59]
	v_lshl_add_u64 v[238:239], v[238:239], 0, s[58:59]
	global_store_dword v[236:237], v218, off
	global_store_dword v[236:237], v219, off offset:2048
	global_store_dword v[238:239], v220, off
	global_store_dword v[238:239], v221, off offset:2048
	s_branch .Lgn_tail
.Lgn_flush:
	s_mov_b32 s0, 1
	s_and_b32 s97, s0, 1
	s_lshl_b32 s97, s97, 13
	v_add_u32_e32 v14, s97, v8
	ds_read_b128 v[16:19], v14
	s_lshr_b32 s97, s97, 4
	v_add_u32_e32 v15, s97, v9
	ds_read_b128 v[20:23], v15
	s_waitcnt lgkmcnt(0)
	global_store_dwordx4 v[10:11], v[16:19], off
	s_cmp_lg_u32 s96, 4
	s_cbranch_scc1 .Lgn_st2
	v_cmp_gt_u32_e32 vcc, 32, v186
	s_and_saveexec_b64 s[30:31], vcc
	global_store_dwordx4 v[12:13], v[20:23], off
	s_or_b64 exec, exec, s[30:31]
